# GEMM K-loop: s_setprio 3 on the loader waves while they issue the next stage's LDS-DMA loads
# baseline (speedup 1.0000x reference)
.Lgk_main:
	s_bitcmp1_b32 s34, 0
	s_cselect_b32 s21, 0, 0xec00
	s_cselect_b32 s5, 0xec00, 0
	s_add_i32 s5, s5, s4
	s_cmp_lt_u32 s12, 4
	s_cbranch_scc0 .Lgk_nl
	s_setprio 3
	s_mov_b32 m0, s5
	v_lshl_add_u64 v[176:177], v[100:101], 0, s[2:3]
	global_load_lds_dwordx4 v[176:177], off
	s_add_i32 m0, s5, 0x1000
	v_lshl_add_u64 v[176:177], v[176:177], 0, s[8:9]
	global_load_lds_dwordx4 v[176:177], off
	s_add_i32 m0, s5, 0x2000
	v_lshl_add_u64 v[176:177], v[104:105], 0, s[2:3]
	global_load_lds_dwordx4 v[176:177], off
	s_add_i32 m0, s5, 0x3000
	v_lshl_add_u64 v[176:177], v[176:177], 0, s[8:9]
	global_load_lds_dwordx4 v[176:177], off
	s_add_i32 m0, s5, 0x4000
	v_lshl_add_u64 v[176:177], v[102:103], 0, s[2:3]
	global_load_lds_dwordx4 v[176:177], off
	s_add_i32 m0, s5, 0x5000
	v_lshl_add_u64 v[176:177], v[176:177], 0, s[8:9]
	global_load_lds_dwordx4 v[176:177], off
	s_add_i32 m0, s5, 0x6000
	v_lshl_add_u64 v[176:177], v[106:107], 0, s[2:3]
	global_load_lds_dwordx4 v[176:177], off
	s_add_i32 m0, s5, 0x7000
	v_lshl_add_u64 v[176:177], v[176:177], 0, s[10:11]
	global_load_lds_dwordx4 v[176:177], off
	s_add_i32 m0, s5, 0x8000
	v_lshl_add_u64 v[176:177], v[112:113], 0, s[2:3]
	global_load_lds_dwordx4 v[176:177], off
	s_add_i32 m0, s5, 0x9000
	v_lshl_add_u64 v[176:177], v[176:177], 0, s[10:11]
	global_load_lds_dwordx4 v[176:177], off
	s_add_i32 m0, s5, 0xa000
	v_lshl_add_u64 v[176:177], v[108:109], 0, s[2:3]
	global_load_lds_dwordx4 v[176:177], off
	s_add_i32 m0, s5, 0xb000
	v_lshl_add_u64 v[176:177], v[176:177], 0, s[10:11]
	global_load_lds_dwordx4 v[176:177], off
	s_add_i32 m0, s5, 0xc000
	v_lshl_add_u64 v[176:177], v[110:111], 0, s[2:3]
	global_load_lds_dwordx4 v[176:177], off
	s_add_i32 m0, s5, 0xd000
	v_lshl_add_u64 v[176:177], v[176:177], 0, s[10:11]
	global_load_lds_dwordx4 v[176:177], off
	s_setprio 0
